# de-serialised loads in phase_lora_prep (mu params as 4 dwordx4) and phase_gd_post (z gate hoisted), on top of transposes prefetch fix
# speedup vs baseline: 1.0059x; 1.0036x over previous
; __device__ void phase_gd_post(const Params& p) {
;     ...
;     for (int m = blockIdx.x * 8 + (tid >> 6); m < MT; m += gridDim.x * 8) {
;         float o[16]; float ss = 0.f;
; #pragma unroll
;         for (int hlf = 0; hlf < 2; ++hlf) { const h16x8 of = ldh8(OF + (size_t)m * 1024 + hc + 8 * hlf), ob = ldh8(OB + (size_t)m * 1024 + hc + 8 * hlf);
; #pragma unroll
;             for (int e = 0; e < 8; ++e) { o[8 * hlf + e] = (float)of[e] + (float)ob[e]; ss += o[8 * hlf + e] * o[8 * hlf + e]; } }
;         const float rr = rsqrtf(red8(ss) * (1.f / 128.f) + 1e-6f);
; #pragma unroll
;         for (int hlf = 0; hlf < 2; ++hlf) { const h16x8 z = ldh8(P + (size_t)m * INC + GDC + 3072 + hc + 8 * hlf); h16x8 r;
.LBB0_168:
	v_ashrrev_i32_e32 v39, 31, v38
	v_lshlrev_b64 v[18:19], 11, v[38:39]
	v_lshl_add_u64 v[46:47], v[40:41], 0, v[18:19]
	v_lshl_add_u64 v[22:23], v[42:43], 0, v[18:19]
	global_load_dwordx4 v[30:33], v[46:47], off
	global_load_dwordx4 v[26:29], v[22:23], off
	global_load_dwordx4 v[18:21], v[46:47], off offset:16
	s_nop 0
	global_load_dwordx4 v[22:25], v[22:23], off offset:16
	v_mov_b32_e32 v45, v0
	v_mov_b64_e32 v[70:71], s[26:27]
	v_mad_i64_i32 v[70:71], s[6:7], v38, s89, v[70:71]
	s_mov_b64 s[6:7], 0x12e07280
	v_lshl_add_u64 v[70:71], v[70:71], 0, v[44:45]
	v_lshl_add_u64 v[72:73], v[70:71], 0, s[6:7]
	global_load_dwordx4 v[74:77], v[72:73], off
	global_load_dwordx4 v[78:81], v[72:73], off offset:16
	s_mov_b32 s5, 0x12e07000
	s_waitcnt vmcnt(5)
	v_cvt_f32_f16_e32 v54, v30
	v_cvt_f32_f16_sdwa v55, v30 dst_sel:DWORD dst_unused:UNUSED_PAD src0_sel:WORD_1
	s_waitcnt vmcnt(3)
	v_cvt_f32_f16_e32 v34, v20
	v_cvt_f32_f16_sdwa v35, v20 dst_sel:DWORD dst_unused:UNUSED_PAD src0_sel:WORD_1
	s_waitcnt vmcnt(2)
	v_cvt_f32_f16_e32 v36, v24
	v_cvt_f32_f16_sdwa v37, v24 dst_sel:DWORD dst_unused:UNUSED_PAD src0_sel:WORD_1
	v_cvt_f32_f16_e32 v56, v26
	v_cvt_f32_f16_sdwa v57, v26 dst_sel:DWORD dst_unused:UNUSED_PAD src0_sel:WORD_1
	v_cvt_f32_f16_e32 v30, v31
	v_pk_add_f32 v[48:49], v[34:35], v[36:37]
	v_mov_b64_e32 v[34:35], s[26:27]
	v_mad_i64_i32 v[34:35], s[6:7], v38, s89, v[34:35]
	v_lshl_add_u64 v[34:35], v[34:35], 0, v[44:45]
	s_mov_b64 s[6:7], 0x12e07280
	v_lshl_add_u64 v[52:53], v[34:35], 0, s[6:7]
	v_add_co_u32_e32 v34, vcc, s5, v34
	v_pk_add_f32 v[54:55], v[54:55], v[56:57]
	s_nop 0
	v_addc_co_u32_e32 v35, vcc, 0, v35, vcc
	s_nop 0
	v_cvt_f32_f16_sdwa v31, v31 dst_sel:DWORD dst_unused:UNUSED_PAD src0_sel:WORD_1
	v_cvt_f32_f16_e32 v26, v27
	v_cvt_f32_f16_sdwa v27, v27 dst_sel:DWORD dst_unused:UNUSED_PAD src0_sel:WORD_1
	v_cvt_f32_f16_e32 v62, v28
	v_cvt_f32_f16_sdwa v63, v28 dst_sel:DWORD dst_unused:UNUSED_PAD src0_sel:WORD_1
	v_cvt_f32_f16_e32 v28, v29
	v_pk_add_f32 v[26:27], v[30:31], v[26:27]
	v_cvt_f32_f16_sdwa v29, v29 dst_sel:DWORD dst_unused:UNUSED_PAD src0_sel:WORD_1
	v_pk_mul_f32 v[58:59], v[54:55], v[54:55]
	v_cvt_f32_f16_e32 v68, v22
	v_cvt_f32_f16_sdwa v69, v22 dst_sel:DWORD dst_unused:UNUSED_PAD src0_sel:WORD_1
	v_cvt_f32_f16_e32 v22, v23
	v_cvt_f32_f16_sdwa v23, v23 dst_sel:DWORD dst_unused:UNUSED_PAD src0_sel:WORD_1
	v_cvt_f32_f16_e32 v20, v21
	v_cvt_f32_f16_sdwa v21, v21 dst_sel:DWORD dst_unused:UNUSED_PAD src0_sel:WORD_1
	v_cvt_f32_f16_e32 v24, v25
	v_cvt_f32_f16_sdwa v25, v25 dst_sel:DWORD dst_unused:UNUSED_PAD src0_sel:WORD_1
	v_pk_mul_f32 v[50:51], v[48:49], v[48:49]
	v_add_u32_e32 v38, s4, v38
	v_pk_add_f32 v[20:21], v[20:21], v[24:25]
	s_nop 0
	v_pk_mul_f32 v[24:25], v[20:21], v[20:21]
	s_waitcnt vmcnt(0)
; __device__ __forceinline__ float fsilu(float x) { return x * fsigmoid(x); }
; __device__ void phase_gd_post(const Params& p) {
;     ...
;         const float rr = rsqrtf(red8(ss) * (1.f / 128.f) + 1e-6f);
; #pragma unroll
;         for (int hlf = 0; hlf < 2; ++hlf) { const h16x8 z = ldh8(P + (size_t)m * INC + GDC + 3072 + hc + 8 * hlf); h16x8 r;
; #pragma unroll
;             for (int e = 0; e < 8; ++e) r[e] = (h16)(o[8 * hlf + e] * rr * nw[8 * hlf + e] * fsilu((float)z[e]));
;             *(h16x8*)(MIX + (size_t)m * 1024 + hc + 8 * hlf) = r; }
	v_mov_b64_e32 v[34:35], v[74:75]
	v_mov_b64_e32 v[36:37], v[76:77]
	v_cvt_f32_f16_e32 v56, v34
	v_cvt_f32_f16_sdwa v57, v34 dst_sel:DWORD dst_unused:UNUSED_PAD src0_sel:WORD_1
	v_cvt_f32_f16_e32 v30, v35
	v_cvt_f32_f16_sdwa v31, v35 dst_sel:DWORD dst_unused:UNUSED_PAD src0_sel:WORD_1
	v_mul_f32_e32 v1, 0xbfb8aa3b, v56
	v_exp_f32_e32 v1, v1
	s_nop 0
	v_add_f32_e32 v1, 1.0, v1
	v_rcp_f32_e32 v60, v1
	v_mul_f32_e32 v1, 0xbfb8aa3b, v57
	v_exp_f32_e32 v1, v1
	s_nop 0
	v_add_f32_e32 v1, 1.0, v1
	v_rcp_f32_e32 v61, v1
	v_mul_f32_e32 v1, 0xbfb8aa3b, v30
	v_exp_f32_e32 v1, v1
	v_pk_mul_f32 v[56:57], v[60:61], v[56:57]
	v_pk_mul_f32 v[60:61], v[26:27], v[26:27]
	v_add_f32_e32 v1, 1.0, v1
	v_rcp_f32_e32 v34, v1
	v_mul_f32_e32 v1, 0xbfb8aa3b, v31
	v_exp_f32_e32 v1, v1
	s_nop 0
	v_add_f32_e32 v1, 1.0, v1
	v_rcp_f32_e32 v35, v1
	s_nop 0
	v_pk_mul_f32 v[30:31], v[34:35], v[30:31]
	v_cvt_f32_f16_e32 v34, v32
	v_cvt_f32_f16_sdwa v35, v32 dst_sel:DWORD dst_unused:UNUSED_PAD src0_sel:WORD_1
	v_cvt_f32_f16_e32 v32, v33
	v_cvt_f32_f16_sdwa v33, v33 dst_sel:DWORD dst_unused:UNUSED_PAD src0_sel:WORD_1
	v_pk_add_f32 v[34:35], v[34:35], v[62:63]
	v_cvt_f32_f16_e32 v62, v36
	v_cvt_f32_f16_sdwa v63, v36 dst_sel:DWORD dst_unused:UNUSED_PAD src0_sel:WORD_1
	v_pk_add_f32 v[28:29], v[32:33], v[28:29]
	v_cvt_f32_f16_e32 v32, v37
	v_mul_f32_e32 v1, 0xbfb8aa3b, v62
	v_exp_f32_e32 v1, v1
	v_cvt_f32_f16_sdwa v33, v37 dst_sel:DWORD dst_unused:UNUSED_PAD src0_sel:WORD_1
	v_pk_mul_f32 v[64:65], v[34:35], v[34:35]
	v_add_f32_e32 v1, 1.0, v1
	v_rcp_f32_e32 v66, v1
	v_mul_f32_e32 v1, 0xbfb8aa3b, v63
	v_exp_f32_e32 v1, v1
	s_nop 0
	v_add_f32_e32 v1, 1.0, v1
	v_rcp_f32_e32 v67, v1
	v_mul_f32_e32 v1, 0xbfb8aa3b, v32
	v_exp_f32_e32 v1, v1
	v_pk_mul_f32 v[62:63], v[66:67], v[62:63]
	v_pk_mul_f32 v[66:67], v[28:29], v[28:29]
	v_add_f32_e32 v1, 1.0, v1
	v_rcp_f32_e32 v36, v1
	v_mul_f32_e32 v1, 0xbfb8aa3b, v33
	v_exp_f32_e32 v1, v1
	s_nop 0
	v_add_f32_e32 v1, 1.0, v1
	v_rcp_f32_e32 v37, v1
	v_add_f32_e32 v1, v58, v59
	v_add_f32_e32 v1, v60, v1
	v_add_f32_e32 v1, v61, v1
	v_pk_mul_f32 v[32:33], v[36:37], v[32:33]
	v_cvt_f32_f16_e32 v36, v18
	v_cvt_f32_f16_sdwa v37, v18 dst_sel:DWORD dst_unused:UNUSED_PAD src0_sel:WORD_1
	v_cvt_f32_f16_e32 v18, v19
	v_cvt_f32_f16_sdwa v19, v19 dst_sel:DWORD dst_unused:UNUSED_PAD src0_sel:WORD_1
	v_add_f32_e32 v1, v64, v1
	v_add_f32_e32 v1, v65, v1
	v_pk_add_f32 v[36:37], v[36:37], v[68:69]
	v_add_f32_e32 v1, v66, v1
	v_pk_mul_f32 v[68:69], v[36:37], v[36:37]
	v_add_f32_e32 v1, v67, v1
	v_pk_add_f32 v[18:19], v[18:19], v[22:23]
	v_add_f32_e32 v1, v68, v1
	v_pk_mul_f32 v[22:23], v[18:19], v[18:19]
	v_add_f32_e32 v1, v69, v1
	v_add_f32_e32 v1, v22, v1
	v_add_f32_e32 v1, v23, v1
	v_add_f32_e32 v1, v50, v1
	v_add_f32_e32 v1, v51, v1
	v_add_f32_e32 v1, v24, v1
	v_add_f32_e32 v1, v25, v1
	s_nop 1
	v_add_f32_dpp v1, v1, v1 quad_perm:[1,0,3,2] row_mask:0xf bank_mask:0xf bound_ctrl:1
	s_nop 1
	v_add_f32_dpp v1, v1, v1 quad_perm:[2,3,0,1] row_mask:0xf bank_mask:0xf bound_ctrl:1
	s_nop 1
	v_add_f32_dpp v1, v1, v1 row_half_mirror row_mask:0xf bank_mask:0xf bound_ctrl:1
	v_fmamk_f32 v1, v1, 0x3c000000, v228
	v_cmp_gt_f32_e32 vcc, s86, v1
	v_mul_f32_e32 v22, 0x4b800000, v1
	s_nop 0
	v_cndmask_b32_e32 v1, v1, v22, vcc
	v_rsq_f32_e32 v1, v1
	s_nop 0
	v_mul_f32_e32 v22, 0x45800000, v1
	v_cndmask_b32_e32 v50, v1, v22, vcc
	v_pk_mul_f32 v[22:23], v[54:55], v[50:51] op_sel_hi:[1,0]
	v_pk_mul_f32 v[24:25], v[26:27], v[50:51] op_sel_hi:[1,0]
	v_pk_mul_f32 v[22:23], v[14:15], v[22:23]
	v_pk_mul_f32 v[24:25], v[16:17], v[24:25]
	v_pk_mul_f32 v[22:23], v[56:57], v[22:23]
	v_pk_mul_f32 v[24:25], v[30:31], v[24:25]
	v_cvt_pk_f16_f32 v22, v22, v23
	v_cvt_pk_f16_f32 v23, v24, v25
	v_pk_mul_f32 v[24:25], v[34:35], v[50:51] op_sel_hi:[1,0]
	v_pk_mul_f32 v[26:27], v[28:29], v[50:51] op_sel_hi:[1,0]
	v_pk_mul_f32 v[24:25], v[10:11], v[24:25]
	v_pk_mul_f32 v[26:27], v[12:13], v[26:27]
	v_pk_mul_f32 v[24:25], v[62:63], v[24:25]
	v_pk_mul_f32 v[26:27], v[32:33], v[26:27]
	v_cvt_pk_f16_f32 v24, v24, v25
	v_cvt_pk_f16_f32 v25, v26, v27
	global_store_dwordx4 v[46:47], v[22:25], off
	s_nop 0
	v_pk_mul_f32 v[30:31], v[36:37], v[50:51] op_sel_hi:[1,0]
	v_pk_mul_f32 v[18:19], v[18:19], v[50:51] op_sel_hi:[1,0]
	v_pk_mul_f32 v[30:31], v[6:7], v[30:31]
	v_pk_mul_f32 v[18:19], v[8:9], v[18:19]
	v_pk_mul_f32 v[20:21], v[20:21], v[50:51] op_sel_hi:[1,0]
	v_cmp_lt_i32_e32 vcc, s84, v38
	v_pk_mul_f32 v[20:21], v[4:5], v[20:21]
	s_or_b64 s[12:13], vcc, s[12:13]
	v_mov_b64_e32 v[22:23], v[78:79]
	v_mov_b64_e32 v[24:25], v[80:81]
	v_cvt_f32_f16_e32 v26, v22
	v_cvt_f32_f16_sdwa v27, v22 dst_sel:DWORD dst_unused:UNUSED_PAD src0_sel:WORD_1
	v_mul_f32_e32 v1, 0xbfb8aa3b, v26
	v_exp_f32_e32 v1, v1
	s_nop 0
	v_add_f32_e32 v1, 1.0, v1
	v_rcp_f32_e32 v28, v1
	v_mul_f32_e32 v1, 0xbfb8aa3b, v27
	v_exp_f32_e32 v1, v1
	s_nop 0
	v_add_f32_e32 v1, 1.0, v1
	v_rcp_f32_e32 v29, v1
	s_nop 0
	v_pk_mul_f32 v[26:27], v[28:29], v[26:27]
	s_nop 0
	v_pk_mul_f32 v[26:27], v[26:27], v[30:31]
	s_nop 0
	v_cvt_pk_f16_f32 v22, v26, v27
	v_cvt_f32_f16_e32 v26, v23
	v_cvt_f32_f16_sdwa v27, v23 dst_sel:DWORD dst_unused:UNUSED_PAD src0_sel:WORD_1
	v_mul_f32_e32 v1, 0xbfb8aa3b, v26
	v_exp_f32_e32 v1, v1
	s_nop 0
	v_add_f32_e32 v1, 1.0, v1
	v_rcp_f32_e32 v28, v1
	v_mul_f32_e32 v1, 0xbfb8aa3b, v27
	v_exp_f32_e32 v1, v1
	s_nop 0
	v_add_f32_e32 v1, 1.0, v1
	v_rcp_f32_e32 v29, v1
	s_nop 0
	v_pk_mul_f32 v[26:27], v[28:29], v[26:27]
	s_nop 0
	v_pk_mul_f32 v[18:19], v[26:27], v[18:19]
	v_pk_mul_f32 v[28:29], v[48:49], v[50:51] op_sel_hi:[1,0]
	v_cvt_pk_f16_f32 v23, v18, v19
	v_cvt_f32_f16_e32 v18, v24
	v_cvt_f32_f16_sdwa v19, v24 dst_sel:DWORD dst_unused:UNUSED_PAD src0_sel:WORD_1
	v_pk_mul_f32 v[28:29], v[2:3], v[28:29]
	v_mul_f32_e32 v1, 0xbfb8aa3b, v18
	v_exp_f32_e32 v1, v1
	s_nop 0
	v_add_f32_e32 v1, 1.0, v1
	v_rcp_f32_e32 v26, v1
	v_mul_f32_e32 v1, 0xbfb8aa3b, v19
	v_exp_f32_e32 v1, v1
	s_nop 0
	v_add_f32_e32 v1, 1.0, v1
	v_rcp_f32_e32 v27, v1
	s_nop 0
	v_pk_mul_f32 v[18:19], v[26:27], v[18:19]
	s_nop 0
	v_pk_mul_f32 v[18:19], v[18:19], v[28:29]
	s_nop 0
	v_cvt_pk_f16_f32 v24, v18, v19
	v_cvt_f32_f16_e32 v18, v25
	v_cvt_f32_f16_sdwa v19, v25 dst_sel:DWORD dst_unused:UNUSED_PAD src0_sel:WORD_1
	v_mul_f32_e32 v1, 0xbfb8aa3b, v18
	v_exp_f32_e32 v1, v1
	s_nop 0
	v_add_f32_e32 v1, 1.0, v1
	v_rcp_f32_e32 v26, v1
	v_mul_f32_e32 v1, 0xbfb8aa3b, v19
	v_exp_f32_e32 v1, v1
	s_nop 0
	v_add_f32_e32 v1, 1.0, v1
	v_rcp_f32_e32 v27, v1
	s_nop 0
	v_pk_mul_f32 v[18:19], v[26:27], v[18:19]
	s_nop 0
	v_pk_mul_f32 v[18:19], v[18:19], v[20:21]
	s_nop 0
	v_cvt_pk_f16_f32 v25, v18, v19
	global_store_dwordx4 v[46:47], v[22:25], off offset:16
	s_andn2_b64 exec, exec, s[12:13]
	s_cbranch_execnz .LBB0_168

; __device__ __forceinline__ float fsigmoid(float x) { return __builtin_amdgcn_rcpf(1.0f + __expf(-x)); }
; __device__ void phase_lora_prep(const Params& p) {
;     ...
;             for (int e = 0; e < 8; ++e) { const float mp = p.mu_prev[col + e], mn = p.mu_next[col + e]; const float x = (float)xc[e];
;                 const float sv = x + mp * ((float)xpv[e] - x) + mn * ((float)xn[e] - x);
;                 float r; if (c < 128) r = 2.0f * fsigmoid(2.0f * sv) - 1.0f; else if (c < 192) r = sv; else r = fsigmoid(sv);
;                 o[e] = (h16)r; }
.LBB0_375:
	s_or_b64 exec, exec, s[0:1]
	v_readlane_b32 s44, v243, 63
	v_lshlrev_b32_e32 v18, 2, v18
	v_readlane_b32 s50, v242, 5
	v_readlane_b32 s51, v242, 6
	v_readlane_b32 s52, v242, 7
	v_readlane_b32 s53, v242, 8
	s_nop 2
	global_load_dwordx4 v[62:65], v18, s[50:51]
	global_load_dwordx4 v[66:69], v18, s[50:51] offset:16
	s_nop 0
	global_load_dwordx4 v[70:73], v18, s[52:53]
	global_load_dwordx4 v[74:77], v18, s[52:53] offset:16
	s_waitcnt vmcnt(4)
	v_cvt_f32_f16_e32 v19, v2
	v_cvt_f32_f16_e32 v22, v10
	v_cvt_f32_f16_e32 v23, v6
	s_movk_i32 s0, 0x7f
	v_cmp_lt_u32_e32 vcc, s0, v21
	v_sub_f32_e32 v22, v22, v19
	v_sub_f32_e32 v19, v23, v19
	v_readlane_b32 s45, v242, 0
	v_readlane_b32 s46, v242, 1
	v_readlane_b32 s47, v242, 2
	v_readlane_b32 s48, v242, 3
	v_readlane_b32 s49, v242, 4
	v_readlane_b32 s54, v242, 9
	v_readlane_b32 s55, v242, 10
	v_readlane_b32 s56, v242, 11
	v_readlane_b32 s57, v242, 12
	v_readlane_b32 s58, v242, 13
	v_readlane_b32 s59, v242, 14
	s_waitcnt vmcnt(3)
	v_fma_mix_f32 v16, v22, v62, v2 op_sel_hi:[0,0,1]
	s_waitcnt vmcnt(0)
	v_fmac_f32_e32 v16, v70, v19
	s_and_saveexec_b64 s[0:1], vcc
	s_xor_b64 s[0:1], exec, s[0:1]
	s_cbranch_execz .LBB0_377
	v_mul_f32_e32 v17, 0xbfb8aa3b, v16
	v_exp_f32_e32 v17, v17
	s_nop 0
	v_add_f32_e32 v17, 1.0, v17
	v_rcp_f32_e32 v17, v17
	s_nop 0
	v_cndmask_b32_e64 v22, v17, v16, s[40:41]

; __device__ __forceinline__ float fsigmoid(float x) { return __builtin_amdgcn_rcpf(1.0f + __expf(-x)); }
; __device__ void phase_lora_prep(const Params& p) {
;     ...
;             for (int e = 0; e < 8; ++e) { const float mp = p.mu_prev[col + e], mn = p.mu_next[col + e]; const float x = (float)xc[e];
;                 const float sv = x + mp * ((float)xpv[e] - x) + mn * ((float)xn[e] - x);
;                 float r; if (c < 128) r = 2.0f * fsigmoid(2.0f * sv) - 1.0f; else if (c < 192) r = sv; else r = fsigmoid(sv);
;                 o[e] = (h16)r; }
.LBB0_379:
	s_or_b64 exec, exec, s[0:1]
	v_readlane_b32 s44, v243, 63
	v_mov_b32_e32 v19, v0
	v_readlane_b32 s50, v242, 5
	v_readlane_b32 s51, v242, 6
	v_readlane_b32 s52, v242, 7
	v_readlane_b32 s53, v242, 8
	v_lshl_add_u64 v[16:17], s[50:51], 0, v[18:19]
	s_nop 0
	v_lshl_add_u64 v[18:19], s[52:53], 0, v[18:19]
	s_nop 0
	v_cvt_f32_f16_sdwa v25, v2 dst_sel:DWORD dst_unused:UNUSED_PAD src0_sel:WORD_1
	v_cvt_f32_f16_sdwa v10, v10 dst_sel:DWORD dst_unused:UNUSED_PAD src0_sel:WORD_1
	v_cvt_f32_f16_sdwa v26, v6 dst_sel:DWORD dst_unused:UNUSED_PAD src0_sel:WORD_1
	v_readlane_b32 s45, v242, 0
	v_readlane_b32 s46, v242, 1
	v_sub_f32_e32 v6, v10, v25
	v_readlane_b32 s47, v242, 2
	v_readlane_b32 s48, v242, 3
	v_readlane_b32 s49, v242, 4
	v_readlane_b32 s54, v242, 9
	v_readlane_b32 s55, v242, 10
	v_readlane_b32 s56, v242, 11
	v_readlane_b32 s57, v242, 12
	v_readlane_b32 s58, v242, 13
	v_readlane_b32 s59, v242, 14
	s_waitcnt vmcnt(1)
	v_fma_mix_f32 v6, v6, v63, v2 op_sel:[0,0,1] op_sel_hi:[0,0,1]
	v_sub_f32_e32 v2, v26, v25
	s_waitcnt vmcnt(0)
	v_fmac_f32_e32 v6, v2, v71
	s_and_saveexec_b64 s[0:1], vcc
	s_xor_b64 s[0:1], exec, s[0:1]
	s_cbranch_execz .LBB0_381
	v_mul_f32_e32 v2, 0xbfb8aa3b, v6
	v_exp_f32_e32 v2, v2
	s_nop 0
	v_add_f32_e32 v2, 1.0, v2
	v_rcp_f32_e32 v2, v2
	s_nop 0
	v_cndmask_b32_e64 v2, v2, v6, s[40:41]

; __device__ __forceinline__ float fsigmoid(float x) { return __builtin_amdgcn_rcpf(1.0f + __expf(-x)); }
; __device__ void phase_lora_prep(const Params& p) {
;     ...
;             for (int e = 0; e < 8; ++e) { const float mp = p.mu_prev[col + e], mn = p.mu_next[col + e]; const float x = (float)xc[e];
;                 const float sv = x + mp * ((float)xpv[e] - x) + mn * ((float)xn[e] - x);
;                 float r; if (c < 128) r = 2.0f * fsigmoid(2.0f * sv) - 1.0f; else if (c < 192) r = sv; else r = fsigmoid(sv);
;                 o[e] = (h16)r; }
.LBB0_383:
	s_or_b64 exec, exec, s[0:1]
	s_nop 0
	s_nop 0
	v_cvt_f32_f16_e32 v24, v3
	v_cvt_f32_f16_e32 v10, v11
	v_cvt_f32_f16_e32 v25, v7
	v_sub_f32_e32 v10, v10, v24
	s_waitcnt vmcnt(1)
	v_fma_mix_f32 v10, v10, v64, v3 op_sel_hi:[0,0,1]
	v_sub_f32_e32 v6, v25, v24
	s_waitcnt vmcnt(0)
	v_fmac_f32_e32 v10, v6, v72
	s_and_saveexec_b64 s[0:1], vcc
	s_xor_b64 s[0:1], exec, s[0:1]
	s_cbranch_execz .LBB0_385
	v_mul_f32_e32 v6, 0xbfb8aa3b, v10
	v_exp_f32_e32 v6, v6
	s_nop 0
	v_add_f32_e32 v6, 1.0, v6
	v_rcp_f32_e32 v6, v6
	s_nop 0
	v_cndmask_b32_e64 v6, v6, v10, s[40:41]

; __device__ __forceinline__ float fsigmoid(float x) { return __builtin_amdgcn_rcpf(1.0f + __expf(-x)); }
; __device__ void phase_lora_prep(const Params& p) {
;     ...
;             for (int e = 0; e < 8; ++e) { const float mp = p.mu_prev[col + e], mn = p.mu_next[col + e]; const float x = (float)xc[e];
;                 const float sv = x + mp * ((float)xpv[e] - x) + mn * ((float)xn[e] - x);
;                 float r; if (c < 128) r = 2.0f * fsigmoid(2.0f * sv) - 1.0f; else if (c < 192) r = sv; else r = fsigmoid(sv);
;                 o[e] = (h16)r; }
.LBB0_387:
	s_or_b64 exec, exec, s[0:1]
	s_nop 0
	s_nop 0
	v_cvt_f32_f16_sdwa v24, v3 dst_sel:DWORD dst_unused:UNUSED_PAD src0_sel:WORD_1
	v_cvt_f32_f16_sdwa v11, v11 dst_sel:DWORD dst_unused:UNUSED_PAD src0_sel:WORD_1
	v_cvt_f32_f16_sdwa v25, v7 dst_sel:DWORD dst_unused:UNUSED_PAD src0_sel:WORD_1
	v_sub_f32_e32 v7, v11, v24
	s_waitcnt vmcnt(1)
	v_fma_mix_f32 v7, v7, v65, v3 op_sel:[0,0,1] op_sel_hi:[0,0,1]
	v_sub_f32_e32 v3, v25, v24
	s_waitcnt vmcnt(0)
	v_fmac_f32_e32 v7, v3, v73
	s_and_saveexec_b64 s[0:1], vcc
	s_xor_b64 s[0:1], exec, s[0:1]
	s_cbranch_execz .LBB0_389
	v_mul_f32_e32 v3, 0xbfb8aa3b, v7
	v_exp_f32_e32 v3, v3
	s_nop 0
	v_add_f32_e32 v3, 1.0, v3
	v_rcp_f32_e32 v3, v3
	s_nop 0
	v_cndmask_b32_e64 v3, v3, v7, s[40:41]

; __device__ __forceinline__ float fsigmoid(float x) { return __builtin_amdgcn_rcpf(1.0f + __expf(-x)); }
; __device__ void phase_lora_prep(const Params& p) {
;     ...
;             for (int e = 0; e < 8; ++e) { const float mp = p.mu_prev[col + e], mn = p.mu_next[col + e]; const float x = (float)xc[e];
;                 const float sv = x + mp * ((float)xpv[e] - x) + mn * ((float)xn[e] - x);
;                 float r; if (c < 128) r = 2.0f * fsigmoid(2.0f * sv) - 1.0f; else if (c < 192) r = sv; else r = fsigmoid(sv);
;                 o[e] = (h16)r; }
.LBB0_391:
	s_or_b64 exec, exec, s[0:1]
	s_nop 0
	s_nop 0
	v_cvt_f32_f16_e32 v23, v4
	v_cvt_f32_f16_e32 v10, v12
	v_cvt_f32_f16_e32 v24, v8
	v_sub_f32_e32 v10, v10, v23
	s_waitcnt vmcnt(1)
	v_fma_mix_f32 v10, v10, v66, v4 op_sel_hi:[0,0,1]
	v_sub_f32_e32 v7, v24, v23
	s_waitcnt vmcnt(0)
	v_fmac_f32_e32 v10, v7, v74
	s_and_saveexec_b64 s[0:1], vcc
	s_xor_b64 s[0:1], exec, s[0:1]
	s_cbranch_execz .LBB0_393
	v_mul_f32_e32 v7, 0xbfb8aa3b, v10
	v_exp_f32_e32 v7, v7
	s_nop 0
	v_add_f32_e32 v7, 1.0, v7
	v_rcp_f32_e32 v7, v7
	s_nop 0
	v_cndmask_b32_e64 v7, v7, v10, s[40:41]

; __device__ __forceinline__ float fsigmoid(float x) { return __builtin_amdgcn_rcpf(1.0f + __expf(-x)); }
; __device__ void phase_lora_prep(const Params& p) {
;     ...
;             for (int e = 0; e < 8; ++e) { const float mp = p.mu_prev[col + e], mn = p.mu_next[col + e]; const float x = (float)xc[e];
;                 const float sv = x + mp * ((float)xpv[e] - x) + mn * ((float)xn[e] - x);
;                 float r; if (c < 128) r = 2.0f * fsigmoid(2.0f * sv) - 1.0f; else if (c < 192) r = sv; else r = fsigmoid(sv);
;                 o[e] = (h16)r; }
.LBB0_395:
	s_or_b64 exec, exec, s[0:1]
	s_nop 0
	s_nop 0
	v_cvt_f32_f16_sdwa v23, v4 dst_sel:DWORD dst_unused:UNUSED_PAD src0_sel:WORD_1
	v_cvt_f32_f16_sdwa v12, v12 dst_sel:DWORD dst_unused:UNUSED_PAD src0_sel:WORD_1
	v_cvt_f32_f16_sdwa v24, v8 dst_sel:DWORD dst_unused:UNUSED_PAD src0_sel:WORD_1
	v_sub_f32_e32 v8, v12, v23
	s_waitcnt vmcnt(1)
	v_fma_mix_f32 v8, v8, v67, v4 op_sel:[0,0,1] op_sel_hi:[0,0,1]
	v_sub_f32_e32 v4, v24, v23
	s_waitcnt vmcnt(0)
	v_fmac_f32_e32 v8, v4, v75
	s_and_saveexec_b64 s[0:1], vcc
	s_xor_b64 s[0:1], exec, s[0:1]
	s_cbranch_execz .LBB0_397
	v_mul_f32_e32 v4, 0xbfb8aa3b, v8
	v_exp_f32_e32 v4, v4
	s_nop 0
	v_add_f32_e32 v4, 1.0, v4
	v_rcp_f32_e32 v4, v4
	s_nop 0
	v_cndmask_b32_e64 v4, v4, v8, s[40:41]

; __device__ __forceinline__ float fsigmoid(float x) { return __builtin_amdgcn_rcpf(1.0f + __expf(-x)); }
; __device__ void phase_lora_prep(const Params& p) {
;     ...
;             for (int e = 0; e < 8; ++e) { const float mp = p.mu_prev[col + e], mn = p.mu_next[col + e]; const float x = (float)xc[e];
;                 const float sv = x + mp * ((float)xpv[e] - x) + mn * ((float)xn[e] - x);
;                 float r; if (c < 128) r = 2.0f * fsigmoid(2.0f * sv) - 1.0f; else if (c < 192) r = sv; else r = fsigmoid(sv);
;                 o[e] = (h16)r; }
.LBB0_399:
	s_or_b64 exec, exec, s[0:1]
	s_nop 0
	s_nop 0
	v_cvt_f32_f16_e32 v12, v5
	v_cvt_f32_f16_e32 v10, v13
	v_cvt_f32_f16_e32 v23, v9
	v_sub_f32_e32 v10, v10, v12
	s_waitcnt vmcnt(1)
	v_fma_mix_f32 v10, v10, v68, v5 op_sel_hi:[0,0,1]
	v_sub_f32_e32 v8, v23, v12
	s_waitcnt vmcnt(0)
	v_fmac_f32_e32 v10, v8, v76
	s_and_saveexec_b64 s[0:1], vcc
	s_xor_b64 s[0:1], exec, s[0:1]
	s_cbranch_execz .LBB0_401
	v_mul_f32_e32 v8, 0xbfb8aa3b, v10
	v_exp_f32_e32 v8, v8
	s_nop 0
	v_add_f32_e32 v8, 1.0, v8
	v_rcp_f32_e32 v8, v8
	s_nop 0
	v_cndmask_b32_e64 v8, v8, v10, s[40:41]

; __device__ __forceinline__ float fsigmoid(float x) { return __builtin_amdgcn_rcpf(1.0f + __expf(-x)); }
; __device__ void phase_lora_prep(const Params& p) {
;     ...
;             for (int e = 0; e < 8; ++e) { const float mp = p.mu_prev[col + e], mn = p.mu_next[col + e]; const float x = (float)xc[e];
;                 const float sv = x + mp * ((float)xpv[e] - x) + mn * ((float)xn[e] - x);
;                 float r; if (c < 128) r = 2.0f * fsigmoid(2.0f * sv) - 1.0f; else if (c < 192) r = sv; else r = fsigmoid(sv);
;                 o[e] = (h16)r; }
.LBB0_403:
	s_or_b64 exec, exec, s[0:1]
	s_nop 0
	s_nop 0
	v_cvt_f32_f16_sdwa v12, v5 dst_sel:DWORD dst_unused:UNUSED_PAD src0_sel:WORD_1
	v_cvt_f32_f16_sdwa v13, v13 dst_sel:DWORD dst_unused:UNUSED_PAD src0_sel:WORD_1
	v_cvt_f32_f16_sdwa v16, v9 dst_sel:DWORD dst_unused:UNUSED_PAD src0_sel:WORD_1
	v_sub_f32_e32 v9, v13, v12
	s_waitcnt vmcnt(1)
	v_fma_mix_f32 v9, v9, v69, v5 op_sel:[0,0,1] op_sel_hi:[0,0,1]
	v_sub_f32_e32 v5, v16, v12
	s_waitcnt vmcnt(0)
	v_fmac_f32_e32 v9, v5, v77
	s_and_saveexec_b64 s[0:1], vcc
	s_xor_b64 s[0:1], exec, s[0:1]
	s_cbranch_execz .LBB0_405
	v_mul_f32_e32 v5, 0xbfb8aa3b, v9
	v_exp_f32_e32 v5, v5
	s_nop 0
	v_add_f32_e32 v5, 1.0, v5
	v_rcp_f32_e32 v5, v5
	s_nop 0
	v_cndmask_b32_e64 v5, v5, v9, s[40:41]
